# scan state waves: dropped the vmcnt(0) between C1 and C2 that only waited for the previous chunk's output stores (no loads in that loop); on top of norm-loop consolidation
# speedup vs baseline: 1.0033x; 1.0033x over previous
; __device__ __forceinline__ unsigned cvt2(float a, float b) { f32x2s v = {a, b}; bf16x2_t r = __builtin_convertvector(v, bf16x2_t); return __builtin_bit_cast(unsigned, r); }
; #define SC_BAR() do { asm volatile("s_waitcnt lgkmcnt(0)" ::: "memory"); __builtin_amdgcn_s_barrier(); asm volatile("" ::: "memory"); } while (0)
; #define LD_C1(buf, s_) do { _Pragma("unroll") for (int ti = 0; ti < 4; ++ti) { LAS const unsigned char* ap_ = lds + SC_QI + (16 * ti + fr) * SC_QS + (32 * (s_) + 4 * fq) * 2; \
;                 faq[buf][ti][0] = *(const LAS v2u*)ap_; faq[buf][ti][1] = *(const LAS v2u*)(ap_ + 32); } } while (0)
; template <bool GLA>
; __device__ __forceinline__ void scan_item2(LAS unsigned char* lds, const bf16* Qd, const bf16* Kd, const bf16* V, bf16* O, const float* EG, int ldqk, int ldv, int b, int h, int dvs, float e_const, int tid) {
;     ...
;         for (int c = 0; c < SEQ / 64; ++c) {
;             SC_BAR();
;             f32x4 oa[4][2];
; #pragma unroll
;             for (int ti = 0; ti < 4; ++ti) { oa[ti][0] = (f32x4){0.f, 0.f, 0.f, 0.f}; oa[ti][1] = (f32x4){0.f, 0.f, 0.f, 0.f}; }
;             v2u faq[2][4][2];
;     ...
;             s16x4 fkt[3][2][2]; bf16x8s bv[2][2];
;     ...
;             LD_C1(0, 0);
; #pragma unroll
;             for (int s_ = 0; s_ < 8; ++s_) {
;                 if (s_ + 1 < 8) LD_C1((s_ + 1) & 1, s_ + 1); else { LD_C2(0, 0); LD_C2(1, 1); }
;                 __builtin_amdgcn_sched_barrier(0);
; #pragma unroll
;                 for (int ct = 0; ct < 2; ++ct) {
;                     v4u sbw; sbw.x = cvt2(st[2 * s_][ct][0], st[2 * s_][ct][1]); sbw.y = cvt2(st[2 * s_][ct][2], st[2 * s_][ct][3]); sbw.z = cvt2(st[2 * s_ + 1][ct][0], st[2 * s_ + 1][ct][1]); sbw.w = cvt2(st[2 * s_ + 1][ct][2], st[2 * s_ + 1][ct][3]);
;                     const bf16x8s sb = __builtin_bit_cast(bf16x8s, sbw);
; #pragma unroll
;                     for (int ti = 0; ti < 4; ++ti) { v4u aw; aw.x = faq[s_ & 1][ti][0].x; aw.y = faq[s_ & 1][ti][0].y; aw.z = faq[s_ & 1][ti][1].x; aw.w = faq[s_ & 1][ti][1].y;
;                         oa[ti][ct] = __builtin_amdgcn_mfma_f32_16x16x32_bf16(sb, __builtin_bit_cast(bf16x8s, aw), oa[ti][ct], 0, 0, 0); } }
;                 __builtin_amdgcn_sched_barrier(0);
;             }
.LBB0_415:
	s_waitcnt lgkmcnt(0)
	s_barrier
	v_add_u32_e32 v198, 0x2000, v248
	v_add_u32_e32 v202, 0x4000, v248
	v_add_u32_e32 v217, 0x6000, v248
	ds_read2_b64 v[130:133], v248 offset1:4
	ds_read2_b64 v[134:137], v198 offset0:32 offset1:36
	ds_read2_b64 v[138:141], v202 offset0:64 offset1:68
	ds_read2_b64 v[142:145], v217 offset0:96 offset1:100
	ds_read2_b64 v[146:149], v248 offset0:8 offset1:12
	ds_read2_b64 v[150:153], v198 offset0:40 offset1:44
	ds_read2_b64 v[154:157], v202 offset0:72 offset1:76
	ds_read2_b64 v[158:161], v217 offset0:104 offset1:108
	v_cvt_pk_bf16_f32 v162, v126, v127
	v_cvt_pk_bf16_f32 v163, v128, v129
	v_cvt_pk_bf16_f32 v164, v118, v119
	v_cvt_pk_bf16_f32 v165, v120, v121
	v_cvt_pk_bf16_f32 v178, v122, v123
	v_cvt_pk_bf16_f32 v179, v124, v125
	v_cvt_pk_bf16_f32 v180, v114, v115
	v_cvt_pk_bf16_f32 v181, v116, v117
	s_waitcnt lgkmcnt(0)
	v_mfma_f32_16x16x32_bf16 v[166:169], v[162:165], v[130:133], 0
	v_mfma_f32_16x16x32_bf16 v[170:173], v[162:165], v[134:137], 0
	v_mfma_f32_16x16x32_bf16 v[174:177], v[162:165], v[138:141], 0
	v_mfma_f32_16x16x32_bf16 v[162:165], v[162:165], v[142:145], 0
	v_mfma_f32_16x16x32_bf16 v[130:133], v[178:181], v[130:133], 0
	v_mfma_f32_16x16x32_bf16 v[134:137], v[178:181], v[134:137], 0
	v_mfma_f32_16x16x32_bf16 v[138:141], v[178:181], v[138:141], 0
	v_mfma_f32_16x16x32_bf16 v[142:145], v[178:181], v[142:145], 0
	ds_read2_b64 v[178:181], v248 offset0:16 offset1:20
	ds_read2_b64 v[182:185], v198 offset0:48 offset1:52
	ds_read2_b64 v[186:189], v202 offset0:80 offset1:84
	ds_read2_b64 v[190:193], v217 offset0:112 offset1:116
	v_cvt_pk_bf16_f32 v194, v110, v111
	v_cvt_pk_bf16_f32 v195, v112, v113
	v_cvt_pk_bf16_f32 v196, v102, v103
	v_cvt_pk_bf16_f32 v197, v104, v105
	s_nop 1
	v_mfma_f32_16x16x32_bf16 v[166:169], v[194:197], v[146:149], v[166:169]
	v_mfma_f32_16x16x32_bf16 v[170:173], v[194:197], v[150:153], v[170:173]
	v_mfma_f32_16x16x32_bf16 v[174:177], v[194:197], v[154:157], v[174:177]
	v_mfma_f32_16x16x32_bf16 v[162:165], v[194:197], v[158:161], v[162:165]
	v_cvt_pk_bf16_f32 v194, v106, v107
	v_cvt_pk_bf16_f32 v195, v108, v109
	v_cvt_pk_bf16_f32 v196, v98, v99
	v_cvt_pk_bf16_f32 v197, v100, v101
	s_nop 1
	v_mfma_f32_16x16x32_bf16 v[130:133], v[194:197], v[146:149], v[130:133]
	v_mfma_f32_16x16x32_bf16 v[134:137], v[194:197], v[150:153], v[134:137]
	v_mfma_f32_16x16x32_bf16 v[138:141], v[194:197], v[154:157], v[138:141]
	v_mfma_f32_16x16x32_bf16 v[142:145], v[194:197], v[158:161], v[142:145]
	ds_read2_b64 v[146:149], v248 offset0:24 offset1:28
	ds_read2_b64 v[150:153], v198 offset0:56 offset1:60
	ds_read2_b64 v[154:157], v202 offset0:88 offset1:92
	ds_read2_b64 v[158:161], v217 offset0:120 offset1:124
	v_cvt_pk_bf16_f32 v194, v94, v95
	v_cvt_pk_bf16_f32 v195, v96, v97
	v_cvt_pk_bf16_f32 v196, v86, v87
	v_cvt_pk_bf16_f32 v197, v88, v89
	s_waitcnt lgkmcnt(0)
	s_nop 0
	v_mfma_f32_16x16x32_bf16 v[166:169], v[194:197], v[178:181], v[166:169]
	v_mfma_f32_16x16x32_bf16 v[170:173], v[194:197], v[182:185], v[170:173]
	v_mfma_f32_16x16x32_bf16 v[174:177], v[194:197], v[186:189], v[174:177]
	v_mfma_f32_16x16x32_bf16 v[162:165], v[194:197], v[190:193], v[162:165]
	v_cvt_pk_bf16_f32 v194, v90, v91
	v_cvt_pk_bf16_f32 v195, v92, v93
	v_cvt_pk_bf16_f32 v196, v82, v83
	v_cvt_pk_bf16_f32 v197, v84, v85
	s_nop 1
	v_mfma_f32_16x16x32_bf16 v[130:133], v[194:197], v[178:181], v[130:133]
	v_mfma_f32_16x16x32_bf16 v[134:137], v[194:197], v[182:185], v[134:137]
	v_mfma_f32_16x16x32_bf16 v[138:141], v[194:197], v[186:189], v[138:141]
	v_mfma_f32_16x16x32_bf16 v[142:145], v[194:197], v[190:193], v[142:145]
	ds_read2_b64 v[178:181], v248 offset0:32 offset1:36
	ds_read2_b64 v[182:185], v198 offset0:64 offset1:68
	ds_read2_b64 v[186:189], v202 offset0:96 offset1:100
	ds_read2_b64 v[190:193], v217 offset0:128 offset1:132
	v_cvt_pk_bf16_f32 v194, v78, v79
	v_cvt_pk_bf16_f32 v195, v80, v81
	v_cvt_pk_bf16_f32 v196, v70, v71
	v_cvt_pk_bf16_f32 v197, v72, v73
	s_nop 1
	v_mfma_f32_16x16x32_bf16 v[166:169], v[194:197], v[146:149], v[166:169]
	v_mfma_f32_16x16x32_bf16 v[170:173], v[194:197], v[150:153], v[170:173]
	v_mfma_f32_16x16x32_bf16 v[174:177], v[194:197], v[154:157], v[174:177]
	v_mfma_f32_16x16x32_bf16 v[162:165], v[194:197], v[158:161], v[162:165]
	v_cvt_pk_bf16_f32 v194, v74, v75
	v_cvt_pk_bf16_f32 v195, v76, v77
	v_cvt_pk_bf16_f32 v196, v66, v67
	v_cvt_pk_bf16_f32 v197, v68, v69
	s_nop 1
	v_mfma_f32_16x16x32_bf16 v[130:133], v[194:197], v[146:149], v[130:133]
	v_mfma_f32_16x16x32_bf16 v[134:137], v[194:197], v[150:153], v[134:137]
	v_mfma_f32_16x16x32_bf16 v[138:141], v[194:197], v[154:157], v[138:141]
	v_mfma_f32_16x16x32_bf16 v[142:145], v[194:197], v[158:161], v[142:145]
	ds_read2_b64 v[146:149], v248 offset0:40 offset1:44
	ds_read2_b64 v[150:153], v198 offset0:72 offset1:76
	ds_read2_b64 v[154:157], v202 offset0:104 offset1:108
	ds_read2_b64 v[158:161], v217 offset0:136 offset1:140
	v_cvt_pk_bf16_f32 v194, v54, v55
	v_cvt_pk_bf16_f32 v195, v56, v57
	v_cvt_pk_bf16_f32 v196, v46, v47
	v_cvt_pk_bf16_f32 v197, v48, v49
	s_waitcnt lgkmcnt(0)
; __device__ __forceinline__ unsigned cvt2(float a, float b) { f32x2s v = {a, b}; bf16x2_t r = __builtin_convertvector(v, bf16x2_t); return __builtin_bit_cast(unsigned, r); }
; template <bool GLA>
; __device__ __forceinline__ void scan_item2(LAS unsigned char* lds, const bf16* Qd, const bf16* Kd, const bf16* V, bf16* O, const float* EG, int ldqk, int ldv, int b, int h, int dvs, float e_const, int tid) {
;     ...
;             for (int s_ = 0; s_ < 8; ++s_) {
;                 if (s_ + 1 < 8) LD_C1((s_ + 1) & 1, s_ + 1); else { LD_C2(0, 0); LD_C2(1, 1); }
;                 __builtin_amdgcn_sched_barrier(0);
; #pragma unroll
;                 for (int ct = 0; ct < 2; ++ct) {
;                     v4u sbw; sbw.x = cvt2(st[2 * s_][ct][0], st[2 * s_][ct][1]); sbw.y = cvt2(st[2 * s_][ct][2], st[2 * s_][ct][3]); sbw.z = cvt2(st[2 * s_ + 1][ct][0], st[2 * s_ + 1][ct][1]); sbw.w = cvt2(st[2 * s_ + 1][ct][2], st[2 * s_ + 1][ct][3]);
;                     const bf16x8s sb = __builtin_bit_cast(bf16x8s, sbw);
; #pragma unroll
;                     for (int ti = 0; ti < 4; ++ti) { v4u aw; aw.x = faq[s_ & 1][ti][0].x; aw.y = faq[s_ & 1][ti][0].y; aw.z = faq[s_ & 1][ti][1].x; aw.w = faq[s_ & 1][ti][1].y;
;                         oa[ti][ct] = __builtin_amdgcn_mfma_f32_16x16x32_bf16(sb, __builtin_bit_cast(bf16x8s, aw), oa[ti][ct], 0, 0, 0); } }
;                 __builtin_amdgcn_sched_barrier(0);
;             }
; #pragma unroll
;             for (int ks = 0; ks < 2; ++ks)
; #pragma unroll
;                 for (int ct = 0; ct < 2; ++ct) { const s16x4 lo = ldtr(lds + SC_VI + (32 * ks + 8 * fq + q4) * SC_VS + (32 * w + 16 * ct + 4 * p4) * 2), hi = ldtr(lds + SC_VI + (32 * ks + 8 * fq + 4 + q4) * SC_VS + (32 * w + 16 * ct + 4 * p4) * 2);
;                     bv[ks][ct] = __builtin_shufflevector(lo, hi, 0, 1, 2, 3, 4, 5, 6, 7); }
; #pragma unroll
;             for (int g = 0; g < 16; ++g) {
;                 if (g + 2 < 16) LD_C2((g + 2) % 3, g + 2);
;                 __builtin_amdgcn_sched_barrier(0);
; #pragma unroll
;                 for (int t = 0; t < 2; ++t) { const bf16x8s ak = __builtin_shufflevector(fkt[g % 3][t][0], fkt[g % 3][t][1], 0, 1, 2, 3, 4, 5, 6, 7);
; #pragma unroll
;                     for (int ct = 0; ct < 2; ++ct) st[2 * (g & 7) + t][ct] = __builtin_amdgcn_mfma_f32_16x16x32_bf16(ak, bv[g >> 3][ct], st[2 * (g & 7) + t][ct], 0, 0, 0); }
	s_nop 0
	v_mfma_f32_16x16x32_bf16 v[166:169], v[194:197], v[178:181], v[166:169]
	v_mfma_f32_16x16x32_bf16 v[170:173], v[194:197], v[182:185], v[170:173]
	v_mfma_f32_16x16x32_bf16 v[174:177], v[194:197], v[186:189], v[174:177]
	v_mfma_f32_16x16x32_bf16 v[162:165], v[194:197], v[190:193], v[162:165]
	v_cvt_pk_bf16_f32 v194, v50, v51
	v_cvt_pk_bf16_f32 v195, v52, v53
	v_cvt_pk_bf16_f32 v196, v42, v43
	v_cvt_pk_bf16_f32 v197, v44, v45
	s_nop 1
	v_mfma_f32_16x16x32_bf16 v[130:133], v[194:197], v[178:181], v[130:133]
	v_mfma_f32_16x16x32_bf16 v[134:137], v[194:197], v[182:185], v[134:137]
	v_mfma_f32_16x16x32_bf16 v[138:141], v[194:197], v[186:189], v[138:141]
	v_mfma_f32_16x16x32_bf16 v[142:145], v[194:197], v[190:193], v[142:145]
	ds_read2_b64 v[178:181], v248 offset0:48 offset1:52
	ds_read2_b64 v[182:185], v198 offset0:80 offset1:84
	ds_read2_b64 v[186:189], v202 offset0:112 offset1:116
	ds_read2_b64 v[190:193], v217 offset0:144 offset1:148
	v_cvt_pk_bf16_f32 v194, v26, v27
	v_cvt_pk_bf16_f32 v195, v28, v29
	v_cvt_pk_bf16_f32 v196, v18, v19
	v_cvt_pk_bf16_f32 v197, v20, v21
	s_nop 1
	v_mfma_f32_16x16x32_bf16 v[166:169], v[194:197], v[146:149], v[166:169]
	v_mfma_f32_16x16x32_bf16 v[170:173], v[194:197], v[150:153], v[170:173]
	v_mfma_f32_16x16x32_bf16 v[174:177], v[194:197], v[154:157], v[174:177]
	v_mfma_f32_16x16x32_bf16 v[162:165], v[194:197], v[158:161], v[162:165]
	v_cvt_pk_bf16_f32 v194, v22, v23
	v_cvt_pk_bf16_f32 v195, v24, v25
	v_cvt_pk_bf16_f32 v196, v14, v15
	v_cvt_pk_bf16_f32 v197, v16, v17
	s_nop 1
	v_mfma_f32_16x16x32_bf16 v[130:133], v[194:197], v[146:149], v[130:133]
	v_mfma_f32_16x16x32_bf16 v[134:137], v[194:197], v[150:153], v[134:137]
	v_mfma_f32_16x16x32_bf16 v[138:141], v[194:197], v[154:157], v[138:141]
	v_mfma_f32_16x16x32_bf16 v[142:145], v[194:197], v[158:161], v[142:145]
	ds_read2_b64 v[194:197], v248 offset0:56 offset1:60
	ds_read2_b64 v[198:201], v198 offset0:88 offset1:92
	ds_read2_b64 v[202:205], v202 offset0:120 offset1:124
	ds_read2_b64 v[244:247], v217 offset0:152 offset1:156
	v_cvt_pk_bf16_f32 v146, v10, v11
	v_cvt_pk_bf16_f32 v147, v12, v13
	v_cvt_pk_bf16_f32 v148, v62, v63
	v_cvt_pk_bf16_f32 v149, v64, v65
	v_cvt_pk_bf16_f32 v158, v6, v7
	v_cvt_pk_bf16_f32 v159, v8, v9
	v_cvt_pk_bf16_f32 v160, v58, v59
	v_cvt_pk_bf16_f32 v161, v60, v61
	s_waitcnt lgkmcnt(0)
	v_mfma_f32_16x16x32_bf16 v[150:153], v[146:149], v[178:181], v[166:169]
	v_mfma_f32_16x16x32_bf16 v[154:157], v[146:149], v[182:185], v[170:173]
	v_mfma_f32_16x16x32_bf16 v[166:169], v[146:149], v[186:189], v[174:177]
	v_mfma_f32_16x16x32_bf16 v[146:149], v[146:149], v[190:193], v[162:165]
	v_mfma_f32_16x16x32_bf16 v[130:133], v[158:161], v[178:181], v[130:133]
	v_mfma_f32_16x16x32_bf16 v[134:137], v[158:161], v[182:185], v[134:137]
	v_mfma_f32_16x16x32_bf16 v[138:141], v[158:161], v[186:189], v[138:141]
	v_mfma_f32_16x16x32_bf16 v[142:145], v[158:161], v[190:193], v[142:145]
	ds_read_b64_tr_b16 v[178:179], v225 offset:33792
	ds_read_b64_tr_b16 v[182:183], v225 offset:33824
	ds_read_b64_tr_b16 v[186:187], v225 offset:33856
	ds_read_b64_tr_b16 v[190:191], v225 offset:33888
	ds_read_b64_tr_b16 v[180:181], v225 offset:35968
	ds_read_b64_tr_b16 v[184:185], v225 offset:36000
	ds_read_b64_tr_b16 v[188:189], v225 offset:36032
	ds_read_b64_tr_b16 v[192:193], v225 offset:36064
	v_cvt_pk_bf16_f32 v162, v38, v39
	v_cvt_pk_bf16_f32 v163, v40, v41
	v_cvt_pk_bf16_f32 v164, v30, v31
	v_cvt_pk_bf16_f32 v165, v32, v33
	s_nop 1
	v_mfma_f32_16x16x32_bf16 v[158:161], v[162:165], v[194:197], v[150:153]
	v_mfma_f32_16x16x32_bf16 v[154:157], v[162:165], v[198:201], v[154:157]
	v_mfma_f32_16x16x32_bf16 v[150:153], v[162:165], v[202:205], v[166:169]
	v_mfma_f32_16x16x32_bf16 v[146:149], v[162:165], v[244:247], v[146:149]
	v_cvt_pk_bf16_f32 v162, v34, v35
	v_cvt_pk_bf16_f32 v163, v36, v37
	v_cvt_pk_bf16_f32 v164, v2, v3
	v_cvt_pk_bf16_f32 v165, v4, v5
	s_nop 1
	v_mfma_f32_16x16x32_bf16 v[174:177], v[162:165], v[194:197], v[130:133]
	v_mfma_f32_16x16x32_bf16 v[170:173], v[162:165], v[198:201], v[134:137]
	v_mfma_f32_16x16x32_bf16 v[166:169], v[162:165], v[202:205], v[138:141]
	v_mfma_f32_16x16x32_bf16 v[138:141], v[162:165], v[244:247], v[142:145]
	ds_read_b64_tr_b16 v[164:165], v215 offset:1152
	ds_read_b64_tr_b16 v[162:163], v215
	s_nop 0
	ds_read_b64_tr_b16 v[144:145], v215 offset:1184
	ds_read_b64_tr_b16 v[142:143], v215 offset:32
	ds_read_b64_tr_b16 v[130:131], v215 offset:9216
	ds_read_b64_tr_b16 v[132:133], v215 offset:10368
	ds_read_b64_tr_b16 v[136:137], v215 offset:10400
	ds_read_b64_tr_b16 v[134:135], v215 offset:9248
	ds_read_b64_tr_b16 v[196:197], v225 offset:36096
	ds_read_b64_tr_b16 v[194:195], v225 offset:33920
	ds_read_b64_tr_b16 v[200:201], v225 offset:36128
	ds_read_b64_tr_b16 v[198:199], v225 offset:33952
	s_waitcnt lgkmcnt(10)
	v_mfma_f32_16x16x32_bf16 v[126:129], v[178:181], v[162:165], v[126:129]
	s_waitcnt lgkmcnt(8)
	v_mfma_f32_16x16x32_bf16 v[122:125], v[178:181], v[142:145], v[122:125]
	v_mfma_f32_16x16x32_bf16 v[118:121], v[182:185], v[162:165], v[118:121]
	v_mfma_f32_16x16x32_bf16 v[114:117], v[182:185], v[142:145], v[114:117]
	ds_read_b64_tr_b16 v[180:181], v225 offset:36160
	ds_read_b64_tr_b16 v[178:179], v225 offset:33984
	ds_read_b64_tr_b16 v[184:185], v225 offset:36192
	ds_read_b64_tr_b16 v[182:183], v225 offset:34016
	v_mfma_f32_16x16x32_bf16 v[110:113], v[186:189], v[162:165], v[110:113]
	v_mfma_f32_16x16x32_bf16 v[106:109], v[186:189], v[142:145], v[106:109]
	v_mfma_f32_16x16x32_bf16 v[102:105], v[190:193], v[162:165], v[102:105]
	v_mfma_f32_16x16x32_bf16 v[98:101], v[190:193], v[142:145], v[98:101]
	ds_read_b64_tr_b16 v[188:189], v225 offset:36224
	ds_read_b64_tr_b16 v[186:187], v225 offset:34048
	ds_read_b64_tr_b16 v[192:193], v225 offset:36256
	ds_read_b64_tr_b16 v[190:191], v225 offset:34080
	s_waitcnt lgkmcnt(10)
; #define LAS __attribute__((address_space(3)))
; #define SC_BAR() do { asm volatile("s_waitcnt lgkmcnt(0)" ::: "memory"); __builtin_amdgcn_s_barrier(); asm volatile("" ::: "memory"); } while (0)
; #define LD_C2(buf, g) do { const int ks_ = (g) >> 3, t0_ = 2 * ((g) & 7); _Pragma("unroll") for (int t = 0; t < 2; ++t) { \
;                 fkt[buf][t][0] = ldtr(lds + SC_KI + (32 * ks_ + 8 * fq + q4) * SC_KS + (16 * (t0_ + t) + 4 * p4) * 2); \
;                 fkt[buf][t][1] = ldtr(lds + SC_KI + (32 * ks_ + 8 * fq + 4 + q4) * SC_KS + (16 * (t0_ + t) + 4 * p4) * 2); } } while (0)
; template <bool GLA>
; __device__ __forceinline__ void scan_item2(LAS unsigned char* lds, const bf16* Qd, const bf16* Kd, const bf16* V, bf16* O, const float* EG, int ldqk, int ldv, int b, int h, int dvs, float e_const, int tid) {
;     ...
; #pragma unroll
;             for (int g = 0; g < 16; ++g) {
;                 if (g + 2 < 16) LD_C2((g + 2) % 3, g + 2);
;                 __builtin_amdgcn_sched_barrier(0);
; #pragma unroll
;                 for (int t = 0; t < 2; ++t) { const bf16x8s ak = __builtin_shufflevector(fkt[g % 3][t][0], fkt[g % 3][t][1], 0, 1, 2, 3, 4, 5, 6, 7);
; #pragma unroll
;                     for (int ct = 0; ct < 2; ++ct) st[2 * (g & 7) + t][ct] = __builtin_amdgcn_mfma_f32_16x16x32_bf16(ak, bv[g >> 3][ct], st[2 * (g & 7) + t][ct], 0, 0, 0); }
;                 __builtin_amdgcn_sched_barrier(0);
;             }
;     ...
; #pragma unroll
;             for (int t = 0; t < 16; ++t) { if (GLA) { const f32x4 e4 = *(const LAS f32x4*)(lds + SC_EI + (16 * t + 4 * fq) * 4); st[t][0] = st[t][0] * e4; st[t][1] = st[t][1] * e4; } else { st[t][0] = st[t][0] * e_const; st[t][1] = st[t][1] * e_const; } }
;             SC_BAR();
	v_mfma_f32_16x16x32_bf16 v[94:97], v[194:197], v[162:165], v[94:97]
	v_mfma_f32_16x16x32_bf16 v[90:93], v[194:197], v[142:145], v[90:93]
	s_waitcnt lgkmcnt(8)
	v_mfma_f32_16x16x32_bf16 v[86:89], v[198:201], v[162:165], v[86:89]
	v_mfma_f32_16x16x32_bf16 v[82:85], v[198:201], v[142:145], v[82:85]
	ds_read_b64_tr_b16 v[196:197], v225 offset:36288
	ds_read_b64_tr_b16 v[194:195], v225 offset:34112
	ds_read_b64_tr_b16 v[200:201], v225 offset:36320
	ds_read_b64_tr_b16 v[198:199], v225 offset:34144
	s_waitcnt lgkmcnt(10)
	v_mfma_f32_16x16x32_bf16 v[78:81], v[178:181], v[162:165], v[78:81]
	v_mfma_f32_16x16x32_bf16 v[74:77], v[178:181], v[142:145], v[74:77]
	s_waitcnt lgkmcnt(8)
	v_mfma_f32_16x16x32_bf16 v[70:73], v[182:185], v[162:165], v[70:73]
	v_mfma_f32_16x16x32_bf16 v[66:69], v[182:185], v[142:145], v[66:69]
	ds_read_b64_tr_b16 v[180:181], v225 offset:36352
	ds_read_b64_tr_b16 v[178:179], v225 offset:34176
	ds_read_b64_tr_b16 v[184:185], v225 offset:36384
	ds_read_b64_tr_b16 v[182:183], v225 offset:34208
	s_waitcnt lgkmcnt(10)
	v_mfma_f32_16x16x32_bf16 v[54:57], v[186:189], v[162:165], v[54:57]
	v_mfma_f32_16x16x32_bf16 v[50:53], v[186:189], v[142:145], v[50:53]
	s_waitcnt lgkmcnt(8)
	v_mfma_f32_16x16x32_bf16 v[46:49], v[190:193], v[162:165], v[46:49]
	v_mfma_f32_16x16x32_bf16 v[42:45], v[190:193], v[142:145], v[42:45]
	ds_read_b64_tr_b16 v[188:189], v225 offset:36416
	ds_read_b64_tr_b16 v[186:187], v225 offset:34240
	ds_read_b64_tr_b16 v[192:193], v225 offset:36448
	ds_read_b64_tr_b16 v[190:191], v225 offset:34272
	s_waitcnt lgkmcnt(10)
	v_mfma_f32_16x16x32_bf16 v[26:29], v[194:197], v[162:165], v[26:29]
	v_mfma_f32_16x16x32_bf16 v[22:25], v[194:197], v[142:145], v[22:25]
	s_waitcnt lgkmcnt(8)
	v_mfma_f32_16x16x32_bf16 v[18:21], v[198:201], v[162:165], v[18:21]
	v_mfma_f32_16x16x32_bf16 v[14:17], v[198:201], v[142:145], v[14:17]
	ds_read_b64_tr_b16 v[196:197], v225 offset:53376
	ds_read_b64_tr_b16 v[194:195], v225 offset:51200
	ds_read_b64_tr_b16 v[200:201], v225 offset:53408
	ds_read_b64_tr_b16 v[198:199], v225 offset:51232
	s_waitcnt lgkmcnt(8)
	v_mfma_f32_16x16x32_bf16 v[62:65], v[182:185], v[162:165], v[62:65]
	v_mfma_f32_16x16x32_bf16 v[58:61], v[182:185], v[142:145], v[58:61]
	v_mfma_f32_16x16x32_bf16 v[202:205], v[178:181], v[162:165], v[10:13]
	v_mfma_f32_16x16x32_bf16 v[178:181], v[178:181], v[142:145], v[6:9]
	s_nop 2
	ds_read_b64_tr_b16 v[8:9], v225 offset:53440
	ds_read_b64_tr_b16 v[6:7], v225 offset:51264
	ds_read_b64_tr_b16 v[12:13], v225 offset:53472
	ds_read_b64_tr_b16 v[10:11], v225 offset:51296
	s_waitcnt lgkmcnt(10)
	v_mfma_f32_16x16x32_bf16 v[182:185], v[186:189], v[162:165], v[38:41]
	v_mfma_f32_16x16x32_bf16 v[186:189], v[186:189], v[142:145], v[34:37]
	s_waitcnt lgkmcnt(8)
	v_mfma_f32_16x16x32_bf16 v[244:247], v[190:193], v[162:165], v[30:33]
	v_mfma_f32_16x16x32_bf16 v[234:237], v[190:193], v[142:145], v[2:5]
	s_nop 2
	ds_read_b64_tr_b16 v[4:5], v225 offset:53504
	ds_read_b64_tr_b16 v[2:3], v225 offset:51328
	ds_read_b64_tr_b16 v[32:33], v225 offset:53536
	ds_read_b64_tr_b16 v[30:31], v225 offset:51360
	s_waitcnt lgkmcnt(10)
	v_mfma_f32_16x16x32_bf16 v[126:129], v[194:197], v[130:133], v[126:129]
	v_mfma_f32_16x16x32_bf16 v[122:125], v[194:197], v[134:137], v[122:125]
	s_waitcnt lgkmcnt(8)
	v_mfma_f32_16x16x32_bf16 v[118:121], v[198:201], v[130:133], v[118:121]
	v_mfma_f32_16x16x32_bf16 v[114:117], v[198:201], v[134:137], v[114:117]
	ds_read_b64_tr_b16 v[36:37], v225 offset:53568
	ds_read_b64_tr_b16 v[34:35], v225 offset:51392
	ds_read_b64_tr_b16 v[40:41], v225 offset:53600
	ds_read_b64_tr_b16 v[38:39], v225 offset:51424
	s_waitcnt lgkmcnt(10)
	v_mfma_f32_16x16x32_bf16 v[110:113], v[6:9], v[130:133], v[110:113]
	v_mfma_f32_16x16x32_bf16 v[106:109], v[6:9], v[134:137], v[106:109]
	s_waitcnt lgkmcnt(8)
	v_mfma_f32_16x16x32_bf16 v[102:105], v[10:13], v[130:133], v[102:105]
	v_mfma_f32_16x16x32_bf16 v[98:101], v[10:13], v[134:137], v[98:101]
	ds_read_b64_tr_b16 v[8:9], v225 offset:53632
	ds_read_b64_tr_b16 v[6:7], v225 offset:51456
	ds_read_b64_tr_b16 v[12:13], v225 offset:53664
	ds_read_b64_tr_b16 v[10:11], v225 offset:51488
	s_waitcnt lgkmcnt(10)
	v_mfma_f32_16x16x32_bf16 v[94:97], v[2:5], v[130:133], v[94:97]
	v_mfma_f32_16x16x32_bf16 v[90:93], v[2:5], v[134:137], v[90:93]
	s_waitcnt lgkmcnt(8)
	v_mfma_f32_16x16x32_bf16 v[86:89], v[30:33], v[130:133], v[86:89]
	v_mfma_f32_16x16x32_bf16 v[82:85], v[30:33], v[134:137], v[82:85]
	ds_read_b64_tr_b16 v[32:33], v225 offset:53696
	ds_read_b64_tr_b16 v[30:31], v225 offset:51520
	ds_read_b64_tr_b16 v[192:193], v225 offset:53728
	ds_read_b64_tr_b16 v[190:191], v225 offset:51552
	s_waitcnt lgkmcnt(10)
	v_mfma_f32_16x16x32_bf16 v[78:81], v[34:37], v[130:133], v[78:81]
	v_mfma_f32_16x16x32_bf16 v[74:77], v[34:37], v[134:137], v[74:77]
	s_waitcnt lgkmcnt(8)
	v_mfma_f32_16x16x32_bf16 v[70:73], v[38:41], v[130:133], v[70:73]
	v_mfma_f32_16x16x32_bf16 v[66:69], v[38:41], v[134:137], v[66:69]
	ds_read_b64_tr_b16 v[40:41], v225 offset:53760
	ds_read_b64_tr_b16 v[38:39], v225 offset:51584
	ds_read_b64_tr_b16 v[196:197], v225 offset:53792
	ds_read_b64_tr_b16 v[194:195], v225 offset:51616
	s_waitcnt lgkmcnt(10)
	v_mfma_f32_16x16x32_bf16 v[54:57], v[6:9], v[130:133], v[54:57]
	v_mfma_f32_16x16x32_bf16 v[50:53], v[6:9], v[134:137], v[50:53]
	s_waitcnt lgkmcnt(8)
	v_mfma_f32_16x16x32_bf16 v[46:49], v[10:13], v[130:133], v[46:49]
	v_mfma_f32_16x16x32_bf16 v[42:45], v[10:13], v[134:137], v[42:45]
	ds_read_b64_tr_b16 v[200:201], v225 offset:53824
	ds_read_b64_tr_b16 v[198:199], v225 offset:51648
	ds_read_b64_tr_b16 v[240:241], v225 offset:53856
	ds_read_b64_tr_b16 v[238:239], v225 offset:51680
	s_waitcnt lgkmcnt(10)
	v_mfma_f32_16x16x32_bf16 v[2:5], v[30:33], v[130:133], v[26:29]
	v_mfma_f32_16x16x32_bf16 v[6:9], v[30:33], v[134:137], v[22:25]
	s_waitcnt lgkmcnt(8)
	v_mfma_f32_16x16x32_bf16 v[10:13], v[190:193], v[130:133], v[18:21]
	v_mfma_f32_16x16x32_bf16 v[14:17], v[190:193], v[134:137], v[14:17]
	s_waitcnt lgkmcnt(6)
	v_mfma_f32_16x16x32_bf16 v[34:37], v[38:41], v[130:133], v[202:205]
	v_mfma_f32_16x16x32_bf16 v[30:33], v[38:41], v[134:137], v[178:181]
	s_waitcnt lgkmcnt(4)
	v_mfma_f32_16x16x32_bf16 v[38:41], v[194:197], v[130:133], v[62:65]
	v_mfma_f32_16x16x32_bf16 v[58:61], v[194:197], v[134:137], v[58:61]
	s_waitcnt lgkmcnt(2)
	v_mfma_f32_16x16x32_bf16 v[178:181], v[198:201], v[130:133], v[182:185]
	v_mfma_f32_16x16x32_bf16 v[182:185], v[198:201], v[134:137], v[186:189]
	s_waitcnt lgkmcnt(0)
	v_mfma_f32_16x16x32_bf16 v[190:193], v[238:241], v[130:133], v[244:247]
	v_mfma_f32_16x16x32_bf16 v[186:189], v[238:241], v[134:137], v[234:237]
	s_waitcnt lgkmcnt(0)
	s_barrier
; #define LAS __attribute__((address_space(3)))
; __device__ __forceinline__ unsigned cvt2(float a, float b) { f32x2s v = {a, b}; bf16x2_t r = __builtin_convertvector(v, bf16x2_t); return __builtin_bit_cast(unsigned, r); }
; #define SC_BAR() do { asm volatile("s_waitcnt lgkmcnt(0)" ::: "memory"); __builtin_amdgcn_s_barrier(); asm volatile("" ::: "memory"); } while (0)
; template <bool GLA>
; __device__ __forceinline__ void scan_item2(LAS unsigned char* lds, const bf16* Qd, const bf16* Kd, const bf16* V, bf16* O, const float* EG, int ldqk, int ldv, int b, int h, int dvs, float e_const, int tid) {
;     ...
;             for (int t = 0; t < 16; ++t) { if (GLA) { const f32x4 e4 = *(const LAS f32x4*)(lds + SC_EI + (16 * t + 4 * fq) * 4); st[t][0] = st[t][0] * e4; st[t][1] = st[t][1] * e4; } else { st[t][0] = st[t][0] * e_const; st[t][1] = st[t][1] * e_const; } }
;             SC_BAR();
; #pragma unroll
;             for (int ks = 0; ks < 2; ++ks) { bf16x8s ap[4];
; #pragma unroll
;                 for (int ti = 0; ti < 4; ++ti) ap[ti] = *(const LAS bf16x8s*)(lds + SC_PI + (16 * ti + fr) * SC_PS + (32 * ks + 8 * fq) * 2);
; #pragma unroll
;                 for (int ti = 0; ti < 4; ++ti)
; #pragma unroll
;                     for (int ct = 0; ct < 2; ++ct) oa[ti][ct] = __builtin_amdgcn_mfma_f32_16x16x32_bf16(bv[ks][ct], ap[ti], oa[ti][ct], 0, 0, 0); }
; #pragma unroll
;             for (int ti = 0; ti < 4; ++ti)
; #pragma unroll
;                 for (int ct = 0; ct < 2; ++ct) { v2u ow; ow.x = cvt2(oa[ti][ct][0], oa[ti][ct][1]); ow.y = cvt2(oa[ti][ct][2], oa[ti][ct][3]);
;                     *(v2u*)((char*)(obase + ((size_t)c * 64 + 16 * ti) * ldv + 16 * ct) + ooff) = ow; }
;         }
;         SC_BAR();
	v_pk_mul_f32 v[22:23], v[220:221], v[6:7]
	v_pk_mul_f32 v[6:7], v[220:221], v[30:31]
	ds_read_b128 v[28:31], v249
	ds_read_b128 v[194:197], v249 offset:64
	s_waitcnt lgkmcnt(1)
	v_mfma_f32_16x16x32_bf16 v[198:201], v[162:165], v[28:31], v[158:161]
	ds_read_b128 v[234:237], v249 offset:5120
	s_nop 1
	ds_read_b128 v[158:161], v249 offset:2624
	v_mov_b32_e32 v219, v218
	v_mfma_f32_16x16x32_bf16 v[174:177], v[142:145], v[28:31], v[174:177]
	ds_read_b128 v[28:31], v249 offset:2560
	v_pk_mul_f32 v[62:63], v[220:221], v[38:39]
	v_pk_mul_f32 v[38:39], v[220:221], v[178:179]
	s_waitcnt lgkmcnt(0)
	v_mfma_f32_16x16x32_bf16 v[202:205], v[162:165], v[28:31], v[154:157]
	v_lshl_add_u64 v[178:179], v[222:223], 0, s[6:7]
	s_nop 1
	ds_read_b128 v[154:157], v249 offset:5184
	s_mov_b32 s0, 0x39f00000
	v_mfma_f32_16x16x32_bf16 v[238:241], v[162:165], v[234:237], v[150:153]
	v_mul_f32_e64 v64, v218, v40
	v_mul_f32_e64 v65, v219, v41
	v_pk_mul_f32 v[40:41], v[218:219], v[180:181]
	v_add_co_u32_e32 v180, vcc, s0, v178
	v_mfma_f32_16x16x32_bf16 v[166:169], v[142:145], v[234:237], v[166:169]
	ds_read_b128 v[234:237], v249 offset:7680
	ds_read_b128 v[150:153], v249 offset:7744
	s_mov_b32 s1, 0x39f20000
	v_mfma_f32_16x16x32_bf16 v[170:173], v[142:145], v[28:31], v[170:173]
	v_addc_co_u32_e32 v181, vcc, 0, v179, vcc
	v_pk_mul_f32 v[18:19], v[220:221], v[10:11]
	s_waitcnt lgkmcnt(1)
	v_mfma_f32_16x16x32_bf16 v[146:149], v[162:165], v[234:237], v[146:149]
	v_mul_f32_e64 v10, v220, v34
	v_mul_f32_e64 v11, v221, v35
	v_pk_mul_f32 v[34:35], v[220:221], v[182:183]
	v_add_co_u32_e32 v182, vcc, s1, v178
	v_mfma_f32_16x16x32_bf16 v[138:141], v[142:145], v[234:237], v[138:141]
	s_mov_b32 s11, 0x39f40000
	v_addc_co_u32_e32 v183, vcc, 0, v179, vcc
	v_mfma_f32_16x16x32_bf16 v[142:145], v[130:133], v[194:197], v[198:201]
	s_add_u32 s6, s6, 0x80000
	v_pk_mul_f32 v[20:21], v[218:219], v[12:13]
	v_pk_mul_f32 v[12:13], v[218:219], v[36:37]
	v_mfma_f32_16x16x32_bf16 v[162:165], v[134:137], v[194:197], v[174:177]
	v_mul_f32_e64 v36, v218, v184
	v_mul_f32_e64 v37, v219, v185
	v_add_co_u32_e32 v184, vcc, s11, v178
	v_mfma_f32_16x16x32_bf16 v[174:177], v[130:133], v[158:161], v[202:205]
	s_mov_b32 s12, 0x39f60000
	v_addc_co_u32_e32 v185, vcc, 0, v179, vcc
	v_mfma_f32_16x16x32_bf16 v[158:161], v[134:137], v[158:161], v[170:173]
	s_addc_u32 s7, s7, 0
	v_pk_mul_f32 v[126:127], v[220:221], v[126:127]
	v_pk_mul_f32 v[122:123], v[220:221], v[122:123]
	v_mfma_f32_16x16x32_bf16 v[170:173], v[130:133], v[154:157], v[238:241]
	v_mul_f32_e64 v118, v220, v118
	v_mul_f32_e64 v119, v221, v119
	v_pk_mul_f32 v[114:115], v[220:221], v[114:115]
	v_pk_mul_f32 v[110:111], v[220:221], v[110:111]
	v_mfma_f32_16x16x32_bf16 v[154:157], v[134:137], v[154:157], v[166:169]
	v_mul_f32_e64 v106, v220, v106
	v_mul_f32_e64 v107, v221, v107
	v_pk_mul_f32 v[102:103], v[220:221], v[102:103]
	v_pk_mul_f32 v[98:99], v[220:221], v[98:99]
	s_waitcnt lgkmcnt(0)
	v_mfma_f32_16x16x32_bf16 v[130:133], v[130:133], v[150:153], v[146:149]
	v_mul_f32_e64 v94, v220, v94
	v_mul_f32_e64 v95, v221, v95
	v_pk_mul_f32 v[90:91], v[220:221], v[90:91]
	v_pk_mul_f32 v[86:87], v[220:221], v[86:87]
	v_mfma_f32_16x16x32_bf16 v[134:137], v[134:137], v[150:153], v[138:141]
	v_mul_f32_e64 v82, v220, v82
	v_mul_f32_e64 v83, v221, v83
	v_pk_mul_f32 v[78:79], v[220:221], v[78:79]
	v_pk_mul_f32 v[74:75], v[220:221], v[74:75]
	v_pk_mul_f32 v[70:71], v[220:221], v[70:71]
	v_pk_mul_f32 v[66:67], v[220:221], v[66:67]
	v_pk_mul_f32 v[54:55], v[220:221], v[54:55]
	v_pk_mul_f32 v[128:129], v[218:219], v[128:129]
	v_pk_mul_f32 v[50:51], v[220:221], v[50:51]
	v_pk_mul_f32 v[124:125], v[218:219], v[124:125]
	v_pk_mul_f32 v[46:47], v[220:221], v[46:47]
	v_pk_mul_f32 v[120:121], v[218:219], v[120:121]
	v_pk_mul_f32 v[42:43], v[220:221], v[42:43]
	v_pk_mul_f32 v[116:117], v[218:219], v[116:117]
	v_pk_mul_f32 v[26:27], v[220:221], v[2:3]
	v_pk_mul_f32 v[112:113], v[218:219], v[112:113]
	v_pk_mul_f32 v[108:109], v[218:219], v[108:109]
	v_pk_mul_f32 v[104:105], v[218:219], v[104:105]
	v_pk_mul_f32 v[14:15], v[220:221], v[14:15]
	v_pk_mul_f32 v[100:101], v[218:219], v[100:101]
	v_pk_mul_f32 v[96:97], v[218:219], v[96:97]
	v_pk_mul_f32 v[92:93], v[218:219], v[92:93]
	v_pk_mul_f32 v[88:89], v[218:219], v[88:89]
	v_pk_mul_f32 v[84:85], v[218:219], v[84:85]
	v_pk_mul_f32 v[80:81], v[218:219], v[80:81]
	v_pk_mul_f32 v[58:59], v[220:221], v[58:59]
	v_pk_mul_f32 v[76:77], v[218:219], v[76:77]
	v_pk_mul_f32 v[72:73], v[218:219], v[72:73]
	v_pk_mul_f32 v[68:69], v[218:219], v[68:69]
	v_pk_mul_f32 v[56:57], v[218:219], v[56:57]
	v_pk_mul_f32 v[52:53], v[218:219], v[52:53]
	v_pk_mul_f32 v[30:31], v[220:221], v[190:191]
	v_pk_mul_f32 v[48:49], v[218:219], v[48:49]
	v_pk_mul_f32 v[2:3], v[220:221], v[186:187]
	v_pk_mul_f32 v[44:45], v[218:219], v[44:45]
	v_pk_mul_f32 v[28:29], v[218:219], v[4:5]
	v_pk_mul_f32 v[24:25], v[218:219], v[8:9]
	v_pk_mul_f32 v[16:17], v[218:219], v[16:17]
	v_pk_mul_f32 v[8:9], v[218:219], v[32:33]
	v_pk_mul_f32 v[60:61], v[218:219], v[60:61]
	v_pk_mul_f32 v[32:33], v[218:219], v[192:193]
	v_pk_mul_f32 v[4:5], v[218:219], v[188:189]
	v_add_co_u32_e32 v166, vcc, s12, v178
	s_cmp_eq_u32 s6, 0x1000000
	v_cvt_pk_bf16_f32 v138, v142, v143
	v_cvt_pk_bf16_f32 v139, v144, v145
	v_addc_co_u32_e32 v167, vcc, 0, v179, vcc
	v_cvt_pk_bf16_f32 v140, v162, v163
	v_cvt_pk_bf16_f32 v141, v164, v165
	v_cvt_pk_bf16_f32 v142, v174, v175
	v_cvt_pk_bf16_f32 v143, v176, v177
	v_cvt_pk_bf16_f32 v144, v158, v159
	v_cvt_pk_bf16_f32 v145, v160, v161
	v_cvt_pk_bf16_f32 v146, v170, v171
	v_cvt_pk_bf16_f32 v147, v172, v173
	v_cvt_pk_bf16_f32 v148, v154, v155
	v_cvt_pk_bf16_f32 v149, v156, v157
	v_cvt_pk_bf16_f32 v130, v130, v131
	v_cvt_pk_bf16_f32 v131, v132, v133
	v_cvt_pk_bf16_f32 v132, v134, v135
	v_cvt_pk_bf16_f32 v133, v136, v137
	global_store_dwordx2 v[180:181], v[138:139], off
	global_store_dwordx2 v[180:181], v[140:141], off offset:32
	global_store_dwordx2 v[182:183], v[142:143], off
	global_store_dwordx2 v[182:183], v[144:145], off offset:32
	global_store_dwordx2 v[184:185], v[146:147], off
	global_store_dwordx2 v[184:185], v[148:149], off offset:32
	global_store_dwordx2 v[166:167], v[130:131], off
	global_store_dwordx2 v[166:167], v[132:133], off offset:32
	s_cbranch_scc0 .LBB0_415
	s_waitcnt lgkmcnt(0)
	s_barrier
	s_branch .LBB0_411

; __device__ __forceinline__ unsigned cvt2(float a, float b) { f32x2s v = {a, b}; bf16x2_t r = __builtin_convertvector(v, bf16x2_t); return __builtin_bit_cast(unsigned, r); }
; #define SC_BAR() do { asm volatile("s_waitcnt lgkmcnt(0)" ::: "memory"); __builtin_amdgcn_s_barrier(); asm volatile("" ::: "memory"); } while (0)
; #define LD_C1(buf, s_) do { _Pragma("unroll") for (int ti = 0; ti < 4; ++ti) { LAS const unsigned char* ap_ = lds + SC_QI + (16 * ti + fr) * SC_QS + (32 * (s_) + 4 * fq) * 2; \
;                 faq[buf][ti][0] = *(const LAS v2u*)ap_; faq[buf][ti][1] = *(const LAS v2u*)(ap_ + 32); } } while (0)
; template <bool GLA>
; __device__ __forceinline__ void scan_item2(LAS unsigned char* lds, const bf16* Qd, const bf16* Kd, const bf16* V, bf16* O, const float* EG, int ldqk, int ldv, int b, int h, int dvs, float e_const, int tid) {
;     ...
;         for (int c = 0; c < SEQ / 64; ++c) {
;             SC_BAR();
;             f32x4 oa[4][2];
; #pragma unroll
;             for (int ti = 0; ti < 4; ++ti) { oa[ti][0] = (f32x4){0.f, 0.f, 0.f, 0.f}; oa[ti][1] = (f32x4){0.f, 0.f, 0.f, 0.f}; }
;             v2u faq[2][4][2];
;     ...
;             s16x4 fkt[3][2][2]; bf16x8s bv[2][2];
;     ...
;             LD_C1(0, 0);
; #pragma unroll
;             for (int s_ = 0; s_ < 8; ++s_) {
;                 if (s_ + 1 < 8) LD_C1((s_ + 1) & 1, s_ + 1); else { LD_C2(0, 0); LD_C2(1, 1); }
;                 __builtin_amdgcn_sched_barrier(0);
; #pragma unroll
;                 for (int ct = 0; ct < 2; ++ct) {
;                     v4u sbw; sbw.x = cvt2(st[2 * s_][ct][0], st[2 * s_][ct][1]); sbw.y = cvt2(st[2 * s_][ct][2], st[2 * s_][ct][3]); sbw.z = cvt2(st[2 * s_ + 1][ct][0], st[2 * s_ + 1][ct][1]); sbw.w = cvt2(st[2 * s_ + 1][ct][2], st[2 * s_ + 1][ct][3]);
;                     const bf16x8s sb = __builtin_bit_cast(bf16x8s, sbw);
; #pragma unroll
;                     for (int ti = 0; ti < 4; ++ti) { v4u aw; aw.x = faq[s_ & 1][ti][0].x; aw.y = faq[s_ & 1][ti][0].y; aw.z = faq[s_ & 1][ti][1].x; aw.w = faq[s_ & 1][ti][1].y;
;                         oa[ti][ct] = __builtin_amdgcn_mfma_f32_16x16x32_bf16(sb, __builtin_bit_cast(bf16x8s, aw), oa[ti][ct], 0, 0, 0); } }
.LBB0_1911:
	s_waitcnt lgkmcnt(0)
	s_barrier
	ds_read2_b64 v[130:133], v217 offset1:4
	ds_read2_b64 v[134:137], v221 offset0:32 offset1:36
	ds_read2_b64 v[138:141], v222 offset0:64 offset1:68
	ds_read2_b64 v[142:145], v223 offset0:96 offset1:100
	ds_read2_b64 v[146:149], v217 offset0:8 offset1:12
	ds_read2_b64 v[150:153], v221 offset0:40 offset1:44
	ds_read2_b64 v[154:157], v222 offset0:72 offset1:76
	ds_read2_b64 v[158:161], v223 offset0:104 offset1:108
	v_cvt_pk_bf16_f32 v162, v6, v7
	v_cvt_pk_bf16_f32 v163, v8, v9
	v_cvt_pk_bf16_f32 v164, v14, v15
	v_cvt_pk_bf16_f32 v165, v16, v17
	v_cvt_pk_bf16_f32 v228, v2, v3
	v_cvt_pk_bf16_f32 v229, v4, v5
	v_cvt_pk_bf16_f32 v230, v10, v11
	v_cvt_pk_bf16_f32 v231, v12, v13
	s_waitcnt lgkmcnt(0)
	v_mfma_f32_16x16x32_bf16 v[166:169], v[162:165], v[130:133], 0
	v_mfma_f32_16x16x32_bf16 v[170:173], v[162:165], v[134:137], 0
	v_mfma_f32_16x16x32_bf16 v[174:177], v[162:165], v[138:141], 0
	v_mfma_f32_16x16x32_bf16 v[162:165], v[162:165], v[142:145], 0
	v_mfma_f32_16x16x32_bf16 v[130:133], v[228:231], v[130:133], 0
	v_mfma_f32_16x16x32_bf16 v[134:137], v[228:231], v[134:137], 0
	v_mfma_f32_16x16x32_bf16 v[138:141], v[228:231], v[138:141], 0
	v_mfma_f32_16x16x32_bf16 v[142:145], v[228:231], v[142:145], 0
	ds_read2_b64 v[228:231], v217 offset0:16 offset1:20
	ds_read2_b64 v[232:235], v221 offset0:48 offset1:52
	ds_read2_b64 v[236:239], v222 offset0:80 offset1:84
	ds_read2_b64 v[240:243], v223 offset0:112 offset1:116
	v_cvt_pk_bf16_f32 v244, v22, v23
	v_cvt_pk_bf16_f32 v245, v24, v25
	v_cvt_pk_bf16_f32 v246, v30, v31
	v_cvt_pk_bf16_f32 v247, v32, v33
	s_nop 1
	v_mfma_f32_16x16x32_bf16 v[166:169], v[244:247], v[146:149], v[166:169]
	v_mfma_f32_16x16x32_bf16 v[170:173], v[244:247], v[150:153], v[170:173]
	v_mfma_f32_16x16x32_bf16 v[174:177], v[244:247], v[154:157], v[174:177]
	v_mfma_f32_16x16x32_bf16 v[162:165], v[244:247], v[158:161], v[162:165]
	v_cvt_pk_bf16_f32 v244, v18, v19
	v_cvt_pk_bf16_f32 v245, v20, v21
	v_cvt_pk_bf16_f32 v246, v26, v27
	v_cvt_pk_bf16_f32 v247, v28, v29
	s_nop 1
	v_mfma_f32_16x16x32_bf16 v[130:133], v[244:247], v[146:149], v[130:133]
	v_mfma_f32_16x16x32_bf16 v[134:137], v[244:247], v[150:153], v[134:137]
	v_mfma_f32_16x16x32_bf16 v[138:141], v[244:247], v[154:157], v[138:141]
	v_mfma_f32_16x16x32_bf16 v[142:145], v[244:247], v[158:161], v[142:145]
	ds_read2_b64 v[146:149], v217 offset0:24 offset1:28
	ds_read2_b64 v[150:153], v221 offset0:56 offset1:60
	ds_read2_b64 v[154:157], v222 offset0:88 offset1:92
	ds_read2_b64 v[158:161], v223 offset0:120 offset1:124
	v_cvt_pk_bf16_f32 v244, v38, v39
	v_cvt_pk_bf16_f32 v245, v40, v41
	v_cvt_pk_bf16_f32 v246, v46, v47
	v_cvt_pk_bf16_f32 v247, v48, v49
	s_waitcnt lgkmcnt(0)
	s_nop 0
	v_mfma_f32_16x16x32_bf16 v[166:169], v[244:247], v[228:231], v[166:169]
	v_mfma_f32_16x16x32_bf16 v[170:173], v[244:247], v[232:235], v[170:173]
	v_mfma_f32_16x16x32_bf16 v[174:177], v[244:247], v[236:239], v[174:177]
	v_mfma_f32_16x16x32_bf16 v[162:165], v[244:247], v[240:243], v[162:165]
	v_cvt_pk_bf16_f32 v244, v34, v35
	v_cvt_pk_bf16_f32 v245, v36, v37
	v_cvt_pk_bf16_f32 v246, v42, v43
	v_cvt_pk_bf16_f32 v247, v44, v45
	s_nop 1
	v_mfma_f32_16x16x32_bf16 v[130:133], v[244:247], v[228:231], v[130:133]
	v_mfma_f32_16x16x32_bf16 v[134:137], v[244:247], v[232:235], v[134:137]
	v_mfma_f32_16x16x32_bf16 v[138:141], v[244:247], v[236:239], v[138:141]
	v_mfma_f32_16x16x32_bf16 v[142:145], v[244:247], v[240:243], v[142:145]
	ds_read2_b64 v[228:231], v217 offset0:32 offset1:36
	ds_read2_b64 v[232:235], v221 offset0:64 offset1:68
	ds_read2_b64 v[236:239], v222 offset0:96 offset1:100
	ds_read2_b64 v[240:243], v223 offset0:128 offset1:132
	v_cvt_pk_bf16_f32 v244, v54, v55
	v_cvt_pk_bf16_f32 v245, v56, v57
	v_cvt_pk_bf16_f32 v246, v62, v63
	v_cvt_pk_bf16_f32 v247, v64, v65
	s_nop 1
	v_mfma_f32_16x16x32_bf16 v[166:169], v[244:247], v[146:149], v[166:169]
	v_mfma_f32_16x16x32_bf16 v[170:173], v[244:247], v[150:153], v[170:173]
	v_mfma_f32_16x16x32_bf16 v[174:177], v[244:247], v[154:157], v[174:177]
	v_mfma_f32_16x16x32_bf16 v[162:165], v[244:247], v[158:161], v[162:165]
	v_cvt_pk_bf16_f32 v244, v50, v51
	v_cvt_pk_bf16_f32 v245, v52, v53
	v_cvt_pk_bf16_f32 v246, v58, v59
	v_cvt_pk_bf16_f32 v247, v60, v61
	s_nop 1
	v_mfma_f32_16x16x32_bf16 v[130:133], v[244:247], v[146:149], v[130:133]
	v_mfma_f32_16x16x32_bf16 v[134:137], v[244:247], v[150:153], v[134:137]
	v_mfma_f32_16x16x32_bf16 v[138:141], v[244:247], v[154:157], v[138:141]
	v_mfma_f32_16x16x32_bf16 v[142:145], v[244:247], v[158:161], v[142:145]
	ds_read2_b64 v[146:149], v217 offset0:40 offset1:44
	ds_read2_b64 v[150:153], v221 offset0:72 offset1:76
	ds_read2_b64 v[154:157], v222 offset0:104 offset1:108
	ds_read2_b64 v[158:161], v223 offset0:136 offset1:140
	v_cvt_pk_bf16_f32 v244, v70, v71
	v_cvt_pk_bf16_f32 v245, v72, v73
	v_cvt_pk_bf16_f32 v246, v78, v79
	v_cvt_pk_bf16_f32 v247, v80, v81
	s_waitcnt lgkmcnt(0)
; __device__ __forceinline__ unsigned cvt2(float a, float b) { f32x2s v = {a, b}; bf16x2_t r = __builtin_convertvector(v, bf16x2_t); return __builtin_bit_cast(unsigned, r); }
; template <bool GLA>
; __device__ __forceinline__ void scan_item2(LAS unsigned char* lds, const bf16* Qd, const bf16* Kd, const bf16* V, bf16* O, const float* EG, int ldqk, int ldv, int b, int h, int dvs, float e_const, int tid) {
;     ...
;             for (int s_ = 0; s_ < 8; ++s_) {
;                 if (s_ + 1 < 8) LD_C1((s_ + 1) & 1, s_ + 1); else { LD_C2(0, 0); LD_C2(1, 1); }
;                 __builtin_amdgcn_sched_barrier(0);
; #pragma unroll
;                 for (int ct = 0; ct < 2; ++ct) {
;                     v4u sbw; sbw.x = cvt2(st[2 * s_][ct][0], st[2 * s_][ct][1]); sbw.y = cvt2(st[2 * s_][ct][2], st[2 * s_][ct][3]); sbw.z = cvt2(st[2 * s_ + 1][ct][0], st[2 * s_ + 1][ct][1]); sbw.w = cvt2(st[2 * s_ + 1][ct][2], st[2 * s_ + 1][ct][3]);
;                     const bf16x8s sb = __builtin_bit_cast(bf16x8s, sbw);
; #pragma unroll
;                     for (int ti = 0; ti < 4; ++ti) { v4u aw; aw.x = faq[s_ & 1][ti][0].x; aw.y = faq[s_ & 1][ti][0].y; aw.z = faq[s_ & 1][ti][1].x; aw.w = faq[s_ & 1][ti][1].y;
;                         oa[ti][ct] = __builtin_amdgcn_mfma_f32_16x16x32_bf16(sb, __builtin_bit_cast(bf16x8s, aw), oa[ti][ct], 0, 0, 0); } }
;                 __builtin_amdgcn_sched_barrier(0);
;             }
; #pragma unroll
;             for (int ks = 0; ks < 2; ++ks)
; #pragma unroll
;                 for (int ct = 0; ct < 2; ++ct) { const s16x4 lo = ldtr(lds + SC_VI + (32 * ks + 8 * fq + q4) * SC_VS + (32 * w + 16 * ct + 4 * p4) * 2), hi = ldtr(lds + SC_VI + (32 * ks + 8 * fq + 4 + q4) * SC_VS + (32 * w + 16 * ct + 4 * p4) * 2);
;                     bv[ks][ct] = __builtin_shufflevector(lo, hi, 0, 1, 2, 3, 4, 5, 6, 7); }
; #pragma unroll
;             for (int g = 0; g < 16; ++g) {
;                 if (g + 2 < 16) LD_C2((g + 2) % 3, g + 2);
;                 __builtin_amdgcn_sched_barrier(0);
; #pragma unroll
;                 for (int t = 0; t < 2; ++t) { const bf16x8s ak = __builtin_shufflevector(fkt[g % 3][t][0], fkt[g % 3][t][1], 0, 1, 2, 3, 4, 5, 6, 7);
; #pragma unroll
;                     for (int ct = 0; ct < 2; ++ct) st[2 * (g & 7) + t][ct] = __builtin_amdgcn_mfma_f32_16x16x32_bf16(ak, bv[g >> 3][ct], st[2 * (g & 7) + t][ct], 0, 0, 0); }
	s_nop 0
	v_mfma_f32_16x16x32_bf16 v[166:169], v[244:247], v[228:231], v[166:169]
	v_mfma_f32_16x16x32_bf16 v[170:173], v[244:247], v[232:235], v[170:173]
	v_mfma_f32_16x16x32_bf16 v[174:177], v[244:247], v[236:239], v[174:177]
	v_mfma_f32_16x16x32_bf16 v[162:165], v[244:247], v[240:243], v[162:165]
	v_cvt_pk_bf16_f32 v244, v66, v67
	v_cvt_pk_bf16_f32 v245, v68, v69
	v_cvt_pk_bf16_f32 v246, v74, v75
	v_cvt_pk_bf16_f32 v247, v76, v77
	s_nop 1
	v_mfma_f32_16x16x32_bf16 v[130:133], v[244:247], v[228:231], v[130:133]
	v_mfma_f32_16x16x32_bf16 v[134:137], v[244:247], v[232:235], v[134:137]
	v_mfma_f32_16x16x32_bf16 v[138:141], v[244:247], v[236:239], v[138:141]
	v_mfma_f32_16x16x32_bf16 v[142:145], v[244:247], v[240:243], v[142:145]
	ds_read2_b64 v[228:231], v217 offset0:48 offset1:52
	ds_read2_b64 v[232:235], v221 offset0:80 offset1:84
	ds_read2_b64 v[236:239], v222 offset0:112 offset1:116
	ds_read2_b64 v[240:243], v223 offset0:144 offset1:148
	v_cvt_pk_bf16_f32 v244, v86, v87
	v_cvt_pk_bf16_f32 v245, v88, v89
	v_cvt_pk_bf16_f32 v246, v94, v95
	v_cvt_pk_bf16_f32 v247, v96, v97
	s_nop 1
	v_mfma_f32_16x16x32_bf16 v[166:169], v[244:247], v[146:149], v[166:169]
	v_mfma_f32_16x16x32_bf16 v[170:173], v[244:247], v[150:153], v[170:173]
	v_mfma_f32_16x16x32_bf16 v[174:177], v[244:247], v[154:157], v[174:177]
	v_mfma_f32_16x16x32_bf16 v[162:165], v[244:247], v[158:161], v[162:165]
	v_cvt_pk_bf16_f32 v244, v82, v83
	v_cvt_pk_bf16_f32 v245, v84, v85
	v_cvt_pk_bf16_f32 v246, v90, v91
	v_cvt_pk_bf16_f32 v247, v92, v93
	s_nop 1
	v_mfma_f32_16x16x32_bf16 v[130:133], v[244:247], v[146:149], v[130:133]
	v_mfma_f32_16x16x32_bf16 v[134:137], v[244:247], v[150:153], v[134:137]
	v_mfma_f32_16x16x32_bf16 v[138:141], v[244:247], v[154:157], v[138:141]
	v_mfma_f32_16x16x32_bf16 v[142:145], v[244:247], v[158:161], v[142:145]
	ds_read2_b64 v[146:149], v217 offset0:56 offset1:60
	ds_read2_b64 v[150:153], v221 offset0:88 offset1:92
	ds_read2_b64 v[244:247], v222 offset0:120 offset1:124
	ds_read2_b64 v[248:251], v223 offset0:152 offset1:156
	v_cvt_pk_bf16_f32 v154, v102, v103
	v_cvt_pk_bf16_f32 v155, v104, v105
	v_cvt_pk_bf16_f32 v156, v110, v111
	v_cvt_pk_bf16_f32 v157, v112, v113
	s_waitcnt lgkmcnt(0)
	s_nop 0
	v_mfma_f32_16x16x32_bf16 v[158:161], v[154:157], v[228:231], v[166:169]
	v_mfma_f32_16x16x32_bf16 v[166:169], v[154:157], v[232:235], v[170:173]
	v_mfma_f32_16x16x32_bf16 v[170:173], v[154:157], v[236:239], v[174:177]
	v_mfma_f32_16x16x32_bf16 v[154:157], v[154:157], v[240:243], v[162:165]
	s_nop 2
	v_cvt_pk_bf16_f32 v162, v98, v99
	v_cvt_pk_bf16_f32 v163, v100, v101
	v_cvt_pk_bf16_f32 v164, v106, v107
	v_cvt_pk_bf16_f32 v165, v108, v109
	s_nop 1
	v_mfma_f32_16x16x32_bf16 v[174:177], v[162:165], v[228:231], v[130:133]
	v_mfma_f32_16x16x32_bf16 v[228:231], v[162:165], v[232:235], v[134:137]
	v_mfma_f32_16x16x32_bf16 v[232:235], v[162:165], v[236:239], v[138:141]
	v_mfma_f32_16x16x32_bf16 v[162:165], v[162:165], v[240:243], v[142:145]
	ds_read_b64_tr_b16 v[236:237], v194 offset:33792
	ds_read_b64_tr_b16 v[240:241], v194 offset:33824
	ds_read_b64_tr_b16 v[204:205], v194 offset:33856
	ds_read_b64_tr_b16 v[208:209], v194 offset:33888
	ds_read_b64_tr_b16 v[238:239], v194 offset:35968
	ds_read_b64_tr_b16 v[242:243], v194 offset:36000
	ds_read_b64_tr_b16 v[206:207], v194 offset:36032
	ds_read_b64_tr_b16 v[210:211], v194 offset:36064
	v_cvt_pk_bf16_f32 v142, v118, v119
	v_cvt_pk_bf16_f32 v143, v120, v121
	v_cvt_pk_bf16_f32 v144, v126, v127
	v_cvt_pk_bf16_f32 v145, v128, v129
	s_nop 1
	v_mfma_f32_16x16x32_bf16 v[134:137], v[142:145], v[150:153], v[166:169]
	s_nop 2
	v_cvt_pk_bf16_f32 v166, v114, v115
	v_cvt_pk_bf16_f32 v167, v116, v117
	v_cvt_pk_bf16_f32 v168, v122, v123
	v_cvt_pk_bf16_f32 v169, v124, v125
	v_mfma_f32_16x16x32_bf16 v[130:133], v[142:145], v[146:149], v[158:161]
	v_mfma_f32_16x16x32_bf16 v[138:141], v[142:145], v[244:247], v[170:173]
	v_mfma_f32_16x16x32_bf16 v[142:145], v[142:145], v[248:251], v[154:157]
	v_mfma_f32_16x16x32_bf16 v[158:161], v[166:169], v[146:149], v[174:177]
	v_mfma_f32_16x16x32_bf16 v[154:157], v[166:169], v[150:153], v[228:231]
	v_mfma_f32_16x16x32_bf16 v[150:153], v[166:169], v[244:247], v[232:235]
	v_mfma_f32_16x16x32_bf16 v[146:149], v[166:169], v[248:251], v[162:165]
	s_nop 2
	ds_read_b64_tr_b16 v[164:165], v1 offset:1152
	ds_read_b64_tr_b16 v[162:163], v1
	ds_read_b64_tr_b16 v[172:173], v1 offset:1184
	ds_read_b64_tr_b16 v[170:171], v1 offset:32
	ds_read_b64_tr_b16 v[166:167], v1 offset:9216
	ds_read_b64_tr_b16 v[168:169], v1 offset:10368
	ds_read_b64_tr_b16 v[176:177], v1 offset:10400
	ds_read_b64_tr_b16 v[174:175], v1 offset:9248
	ds_read_b64_tr_b16 v[230:231], v194 offset:36096
	ds_read_b64_tr_b16 v[228:229], v194 offset:33920
	ds_read_b64_tr_b16 v[234:235], v194 offset:36128
	ds_read_b64_tr_b16 v[232:233], v194 offset:33952
	s_waitcnt lgkmcnt(10)
	v_mfma_f32_16x16x32_bf16 v[6:9], v[236:239], v[162:165], v[6:9]
	s_waitcnt lgkmcnt(8)
	v_mfma_f32_16x16x32_bf16 v[2:5], v[236:239], v[170:173], v[2:5]
	v_mfma_f32_16x16x32_bf16 v[14:17], v[240:243], v[162:165], v[14:17]
	v_mfma_f32_16x16x32_bf16 v[10:13], v[240:243], v[170:173], v[10:13]
	ds_read_b64_tr_b16 v[238:239], v194 offset:36160
	ds_read_b64_tr_b16 v[236:237], v194 offset:33984
	ds_read_b64_tr_b16 v[242:243], v194 offset:36192
	ds_read_b64_tr_b16 v[240:241], v194 offset:34016
	v_mfma_f32_16x16x32_bf16 v[22:25], v[204:207], v[162:165], v[22:25]
	v_mfma_f32_16x16x32_bf16 v[18:21], v[204:207], v[170:173], v[18:21]
	v_mfma_f32_16x16x32_bf16 v[30:33], v[208:211], v[162:165], v[30:33]
	v_mfma_f32_16x16x32_bf16 v[26:29], v[208:211], v[170:173], v[26:29]
	ds_read_b64_tr_b16 v[206:207], v194 offset:36224
	ds_read_b64_tr_b16 v[204:205], v194 offset:34048
	ds_read_b64_tr_b16 v[210:211], v194 offset:36256
	ds_read_b64_tr_b16 v[208:209], v194 offset:34080
	s_waitcnt lgkmcnt(10)
; #define LD_C2(buf, g) do { const int ks_ = (g) >> 3, t0_ = 2 * ((g) & 7); _Pragma("unroll") for (int t = 0; t < 2; ++t) { \
;                 fkt[buf][t][0] = ldtr(lds + SC_KI + (32 * ks_ + 8 * fq + q4) * SC_KS + (16 * (t0_ + t) + 4 * p4) * 2); \
;                 fkt[buf][t][1] = ldtr(lds + SC_KI + (32 * ks_ + 8 * fq + 4 + q4) * SC_KS + (16 * (t0_ + t) + 4 * p4) * 2); } } while (0)
; template <bool GLA>
; __device__ __forceinline__ void scan_item2(LAS unsigned char* lds, const bf16* Qd, const bf16* Kd, const bf16* V, bf16* O, const float* EG, int ldqk, int ldv, int b, int h, int dvs, float e_const, int tid) {
;     ...
; #pragma unroll
;             for (int g = 0; g < 16; ++g) {
;                 if (g + 2 < 16) LD_C2((g + 2) % 3, g + 2);
;                 __builtin_amdgcn_sched_barrier(0);
; #pragma unroll
;                 for (int t = 0; t < 2; ++t) { const bf16x8s ak = __builtin_shufflevector(fkt[g % 3][t][0], fkt[g % 3][t][1], 0, 1, 2, 3, 4, 5, 6, 7);
; #pragma unroll
;                     for (int ct = 0; ct < 2; ++ct) st[2 * (g & 7) + t][ct] = __builtin_amdgcn_mfma_f32_16x16x32_bf16(ak, bv[g >> 3][ct], st[2 * (g & 7) + t][ct], 0, 0, 0); }
;                 __builtin_amdgcn_sched_barrier(0);
;             }
	v_mfma_f32_16x16x32_bf16 v[38:41], v[228:231], v[162:165], v[38:41]
	v_mfma_f32_16x16x32_bf16 v[34:37], v[228:231], v[170:173], v[34:37]
	s_waitcnt lgkmcnt(8)
	v_mfma_f32_16x16x32_bf16 v[46:49], v[232:235], v[162:165], v[46:49]
	v_mfma_f32_16x16x32_bf16 v[42:45], v[232:235], v[170:173], v[42:45]
	ds_read_b64_tr_b16 v[230:231], v194 offset:36288
	ds_read_b64_tr_b16 v[228:229], v194 offset:34112
	ds_read_b64_tr_b16 v[234:235], v194 offset:36320
	ds_read_b64_tr_b16 v[232:233], v194 offset:34144
	s_waitcnt lgkmcnt(10)
	v_mfma_f32_16x16x32_bf16 v[54:57], v[236:239], v[162:165], v[54:57]
	v_mfma_f32_16x16x32_bf16 v[50:53], v[236:239], v[170:173], v[50:53]
	s_waitcnt lgkmcnt(8)
	v_mfma_f32_16x16x32_bf16 v[62:65], v[240:243], v[162:165], v[62:65]
	v_mfma_f32_16x16x32_bf16 v[58:61], v[240:243], v[170:173], v[58:61]
	ds_read_b64_tr_b16 v[238:239], v194 offset:36352
	ds_read_b64_tr_b16 v[236:237], v194 offset:34176
	ds_read_b64_tr_b16 v[242:243], v194 offset:36384
	ds_read_b64_tr_b16 v[240:241], v194 offset:34208
	s_waitcnt lgkmcnt(10)
	v_mfma_f32_16x16x32_bf16 v[70:73], v[204:207], v[162:165], v[70:73]
	v_mfma_f32_16x16x32_bf16 v[66:69], v[204:207], v[170:173], v[66:69]
	s_waitcnt lgkmcnt(8)
	v_mfma_f32_16x16x32_bf16 v[78:81], v[208:211], v[162:165], v[78:81]
	v_mfma_f32_16x16x32_bf16 v[74:77], v[208:211], v[170:173], v[74:77]
	ds_read_b64_tr_b16 v[206:207], v194 offset:36416
	ds_read_b64_tr_b16 v[204:205], v194 offset:34240
	ds_read_b64_tr_b16 v[210:211], v194 offset:36448
	ds_read_b64_tr_b16 v[208:209], v194 offset:34272
	s_waitcnt lgkmcnt(10)
	v_mfma_f32_16x16x32_bf16 v[86:89], v[228:231], v[162:165], v[86:89]
	v_mfma_f32_16x16x32_bf16 v[82:85], v[228:231], v[170:173], v[82:85]
	s_waitcnt lgkmcnt(8)
	v_mfma_f32_16x16x32_bf16 v[94:97], v[232:235], v[162:165], v[94:97]
	v_mfma_f32_16x16x32_bf16 v[90:93], v[232:235], v[170:173], v[90:93]
	ds_read_b64_tr_b16 v[230:231], v194 offset:53376
	ds_read_b64_tr_b16 v[228:229], v194 offset:51200
	ds_read_b64_tr_b16 v[234:235], v194 offset:53408
	ds_read_b64_tr_b16 v[232:233], v194 offset:51232
	s_waitcnt lgkmcnt(10)
	v_mfma_f32_16x16x32_bf16 v[102:105], v[236:239], v[162:165], v[102:105]
	v_mfma_f32_16x16x32_bf16 v[98:101], v[236:239], v[170:173], v[98:101]
	s_waitcnt lgkmcnt(8)
	v_mfma_f32_16x16x32_bf16 v[110:113], v[240:243], v[162:165], v[110:113]
	v_mfma_f32_16x16x32_bf16 v[106:109], v[240:243], v[170:173], v[106:109]
	ds_read_b64_tr_b16 v[238:239], v194 offset:53440
	ds_read_b64_tr_b16 v[236:237], v194 offset:51264
	ds_read_b64_tr_b16 v[242:243], v194 offset:53472
	ds_read_b64_tr_b16 v[240:241], v194 offset:51296
	s_waitcnt lgkmcnt(10)
	v_mfma_f32_16x16x32_bf16 v[118:121], v[204:207], v[162:165], v[118:121]
	v_mfma_f32_16x16x32_bf16 v[114:117], v[204:207], v[170:173], v[114:117]
	s_waitcnt lgkmcnt(8)
	v_mfma_f32_16x16x32_bf16 v[126:129], v[208:211], v[162:165], v[126:129]
	v_mfma_f32_16x16x32_bf16 v[122:125], v[208:211], v[170:173], v[122:125]
	ds_read_b64_tr_b16 v[206:207], v194 offset:53504
	ds_read_b64_tr_b16 v[204:205], v194 offset:51328
	ds_read_b64_tr_b16 v[210:211], v194 offset:53536
	ds_read_b64_tr_b16 v[208:209], v194 offset:51360
	s_waitcnt lgkmcnt(10)
	v_mfma_f32_16x16x32_bf16 v[6:9], v[228:231], v[166:169], v[6:9]
	v_mfma_f32_16x16x32_bf16 v[2:5], v[228:231], v[174:177], v[2:5]
	s_waitcnt lgkmcnt(8)
	v_mfma_f32_16x16x32_bf16 v[14:17], v[232:235], v[166:169], v[14:17]
	v_mfma_f32_16x16x32_bf16 v[10:13], v[232:235], v[174:177], v[10:13]
	ds_read_b64_tr_b16 v[230:231], v194 offset:53568
	ds_read_b64_tr_b16 v[228:229], v194 offset:51392
	ds_read_b64_tr_b16 v[234:235], v194 offset:53600
	ds_read_b64_tr_b16 v[232:233], v194 offset:51424
	s_waitcnt lgkmcnt(10)
	v_mfma_f32_16x16x32_bf16 v[22:25], v[236:239], v[166:169], v[22:25]
	v_mfma_f32_16x16x32_bf16 v[18:21], v[236:239], v[174:177], v[18:21]
	s_waitcnt lgkmcnt(8)
	v_mfma_f32_16x16x32_bf16 v[30:33], v[240:243], v[166:169], v[30:33]
	v_mfma_f32_16x16x32_bf16 v[26:29], v[240:243], v[174:177], v[26:29]
	ds_read_b64_tr_b16 v[238:239], v194 offset:53632
	ds_read_b64_tr_b16 v[236:237], v194 offset:51456
	ds_read_b64_tr_b16 v[242:243], v194 offset:53664
	ds_read_b64_tr_b16 v[240:241], v194 offset:51488
	s_waitcnt lgkmcnt(10)
	v_mfma_f32_16x16x32_bf16 v[38:41], v[204:207], v[166:169], v[38:41]
	v_mfma_f32_16x16x32_bf16 v[34:37], v[204:207], v[174:177], v[34:37]
	s_waitcnt lgkmcnt(8)
	v_mfma_f32_16x16x32_bf16 v[46:49], v[208:211], v[166:169], v[46:49]
	v_mfma_f32_16x16x32_bf16 v[42:45], v[208:211], v[174:177], v[42:45]
	ds_read_b64_tr_b16 v[206:207], v194 offset:53696
	ds_read_b64_tr_b16 v[204:205], v194 offset:51520
	ds_read_b64_tr_b16 v[210:211], v194 offset:53728
	ds_read_b64_tr_b16 v[208:209], v194 offset:51552
	s_waitcnt lgkmcnt(10)
	v_mfma_f32_16x16x32_bf16 v[54:57], v[228:231], v[166:169], v[54:57]
	v_mfma_f32_16x16x32_bf16 v[50:53], v[228:231], v[174:177], v[50:53]
	s_waitcnt lgkmcnt(8)
	v_mfma_f32_16x16x32_bf16 v[62:65], v[232:235], v[166:169], v[62:65]
	v_mfma_f32_16x16x32_bf16 v[58:61], v[232:235], v[174:177], v[58:61]
	ds_read_b64_tr_b16 v[230:231], v194 offset:53760
	ds_read_b64_tr_b16 v[228:229], v194 offset:51584
	ds_read_b64_tr_b16 v[234:235], v194 offset:53792
	ds_read_b64_tr_b16 v[232:233], v194 offset:51616
	s_waitcnt lgkmcnt(10)
	v_mfma_f32_16x16x32_bf16 v[70:73], v[236:239], v[166:169], v[70:73]
	v_mfma_f32_16x16x32_bf16 v[66:69], v[236:239], v[174:177], v[66:69]
	s_waitcnt lgkmcnt(8)
	v_mfma_f32_16x16x32_bf16 v[78:81], v[240:243], v[166:169], v[78:81]
	v_mfma_f32_16x16x32_bf16 v[74:77], v[240:243], v[174:177], v[74:77]
	ds_read_b64_tr_b16 v[238:239], v194 offset:53824
	ds_read_b64_tr_b16 v[236:237], v194 offset:51648
	ds_read_b64_tr_b16 v[242:243], v194 offset:53856
	ds_read_b64_tr_b16 v[240:241], v194 offset:51680
	s_waitcnt lgkmcnt(10)
; #define LAS __attribute__((address_space(3)))
; #define SC_BAR() do { asm volatile("s_waitcnt lgkmcnt(0)" ::: "memory"); __builtin_amdgcn_s_barrier(); asm volatile("" ::: "memory"); } while (0)
; template <bool GLA>
; __device__ __forceinline__ void scan_item2(LAS unsigned char* lds, const bf16* Qd, const bf16* Kd, const bf16* V, bf16* O, const float* EG, int ldqk, int ldv, int b, int h, int dvs, float e_const, int tid) {
;     ...
;                     for (int ct = 0; ct < 2; ++ct) st[2 * (g & 7) + t][ct] = __builtin_amdgcn_mfma_f32_16x16x32_bf16(ak, bv[g >> 3][ct], st[2 * (g & 7) + t][ct], 0, 0, 0); }
;                 __builtin_amdgcn_sched_barrier(0);
;             }
;     ...
; #pragma unroll
;             for (int t = 0; t < 16; ++t) { if (GLA) { const f32x4 e4 = *(const LAS f32x4*)(lds + SC_EI + (16 * t + 4 * fq) * 4); st[t][0] = st[t][0] * e4; st[t][1] = st[t][1] * e4; } else { st[t][0] = st[t][0] * e_const; st[t][1] = st[t][1] * e_const; } }
;             SC_BAR();
	v_mfma_f32_16x16x32_bf16 v[86:89], v[204:207], v[166:169], v[86:89]
	v_mfma_f32_16x16x32_bf16 v[82:85], v[204:207], v[174:177], v[82:85]
	s_waitcnt lgkmcnt(8)
	v_mfma_f32_16x16x32_bf16 v[94:97], v[208:211], v[166:169], v[94:97]
	v_mfma_f32_16x16x32_bf16 v[90:93], v[208:211], v[174:177], v[90:93]
	s_waitcnt lgkmcnt(6)
	v_mfma_f32_16x16x32_bf16 v[102:105], v[228:231], v[166:169], v[102:105]
	v_mfma_f32_16x16x32_bf16 v[98:101], v[228:231], v[174:177], v[98:101]
	s_waitcnt lgkmcnt(4)
	v_mfma_f32_16x16x32_bf16 v[110:113], v[232:235], v[166:169], v[110:113]
	v_mfma_f32_16x16x32_bf16 v[106:109], v[232:235], v[174:177], v[106:109]
	s_waitcnt lgkmcnt(2)
	v_mfma_f32_16x16x32_bf16 v[118:121], v[236:239], v[166:169], v[118:121]
	v_mfma_f32_16x16x32_bf16 v[114:117], v[236:239], v[174:177], v[114:117]
	s_waitcnt lgkmcnt(0)
	v_mfma_f32_16x16x32_bf16 v[126:129], v[240:243], v[166:169], v[126:129]
	v_mfma_f32_16x16x32_bf16 v[122:125], v[240:243], v[174:177], v[122:125]
	ds_read_b128 v[204:207], v218
	s_waitcnt lgkmcnt(0)
	v_pk_mul_f32 v[8:9], v[8:9], v[206:207]
	v_pk_mul_f32 v[6:7], v[6:7], v[204:205]
	v_pk_mul_f32 v[4:5], v[4:5], v[206:207]
	v_pk_mul_f32 v[2:3], v[2:3], v[204:205]
	ds_read_b128 v[204:207], v218 offset:64
	s_waitcnt lgkmcnt(0)
	v_pk_mul_f32 v[16:17], v[16:17], v[206:207]
	v_pk_mul_f32 v[14:15], v[14:15], v[204:205]
	v_pk_mul_f32 v[12:13], v[12:13], v[206:207]
	v_pk_mul_f32 v[10:11], v[10:11], v[204:205]
	ds_read_b128 v[204:207], v218 offset:128
	s_waitcnt lgkmcnt(0)
	v_pk_mul_f32 v[24:25], v[24:25], v[206:207]
	v_pk_mul_f32 v[22:23], v[22:23], v[204:205]
	v_pk_mul_f32 v[20:21], v[20:21], v[206:207]
	v_pk_mul_f32 v[18:19], v[18:19], v[204:205]
	ds_read_b128 v[204:207], v218 offset:192
	s_waitcnt lgkmcnt(0)
	v_pk_mul_f32 v[32:33], v[32:33], v[206:207]
	v_pk_mul_f32 v[30:31], v[30:31], v[204:205]
	v_pk_mul_f32 v[28:29], v[28:29], v[206:207]
	v_pk_mul_f32 v[26:27], v[26:27], v[204:205]
	ds_read_b128 v[204:207], v218 offset:256
	s_waitcnt lgkmcnt(0)
	v_pk_mul_f32 v[40:41], v[40:41], v[206:207]
	v_pk_mul_f32 v[38:39], v[38:39], v[204:205]
	v_pk_mul_f32 v[36:37], v[36:37], v[206:207]
	v_pk_mul_f32 v[34:35], v[34:35], v[204:205]
	ds_read_b128 v[204:207], v218 offset:320
	s_waitcnt lgkmcnt(0)
	v_pk_mul_f32 v[48:49], v[48:49], v[206:207]
	v_pk_mul_f32 v[46:47], v[46:47], v[204:205]
	v_pk_mul_f32 v[44:45], v[44:45], v[206:207]
	v_pk_mul_f32 v[42:43], v[42:43], v[204:205]
	ds_read_b128 v[204:207], v218 offset:384
	s_waitcnt lgkmcnt(0)
	v_pk_mul_f32 v[56:57], v[56:57], v[206:207]
	v_pk_mul_f32 v[54:55], v[54:55], v[204:205]
	v_pk_mul_f32 v[52:53], v[52:53], v[206:207]
	v_pk_mul_f32 v[50:51], v[50:51], v[204:205]
	ds_read_b128 v[204:207], v218 offset:448
	s_waitcnt lgkmcnt(0)
	v_pk_mul_f32 v[64:65], v[64:65], v[206:207]
	v_pk_mul_f32 v[62:63], v[62:63], v[204:205]
	v_pk_mul_f32 v[60:61], v[60:61], v[206:207]
	v_pk_mul_f32 v[58:59], v[58:59], v[204:205]
	ds_read_b128 v[204:207], v218 offset:512
	s_waitcnt lgkmcnt(0)
	v_pk_mul_f32 v[72:73], v[72:73], v[206:207]
	v_pk_mul_f32 v[70:71], v[70:71], v[204:205]
	v_pk_mul_f32 v[68:69], v[68:69], v[206:207]
	v_pk_mul_f32 v[66:67], v[66:67], v[204:205]
	ds_read_b128 v[204:207], v218 offset:576
	s_waitcnt lgkmcnt(0)
	v_pk_mul_f32 v[80:81], v[80:81], v[206:207]
	v_pk_mul_f32 v[78:79], v[78:79], v[204:205]
	v_pk_mul_f32 v[76:77], v[76:77], v[206:207]
	v_pk_mul_f32 v[74:75], v[74:75], v[204:205]
	ds_read_b128 v[204:207], v218 offset:640
	s_waitcnt lgkmcnt(0)
	v_pk_mul_f32 v[88:89], v[88:89], v[206:207]
	v_pk_mul_f32 v[86:87], v[86:87], v[204:205]
	v_pk_mul_f32 v[84:85], v[84:85], v[206:207]
	v_pk_mul_f32 v[82:83], v[82:83], v[204:205]
	ds_read_b128 v[204:207], v218 offset:704
	s_waitcnt lgkmcnt(0)
	v_pk_mul_f32 v[96:97], v[96:97], v[206:207]
	v_pk_mul_f32 v[94:95], v[94:95], v[204:205]
	v_pk_mul_f32 v[92:93], v[92:93], v[206:207]
	v_pk_mul_f32 v[90:91], v[90:91], v[204:205]
	ds_read_b128 v[204:207], v218 offset:768
	s_waitcnt lgkmcnt(0)
	v_pk_mul_f32 v[104:105], v[104:105], v[206:207]
	v_pk_mul_f32 v[102:103], v[102:103], v[204:205]
	v_pk_mul_f32 v[100:101], v[100:101], v[206:207]
	v_pk_mul_f32 v[98:99], v[98:99], v[204:205]
	ds_read_b128 v[204:207], v218 offset:832
	s_waitcnt lgkmcnt(0)
	v_pk_mul_f32 v[112:113], v[112:113], v[206:207]
	v_pk_mul_f32 v[110:111], v[110:111], v[204:205]
	v_pk_mul_f32 v[108:109], v[108:109], v[206:207]
	v_pk_mul_f32 v[106:107], v[106:107], v[204:205]
	ds_read_b128 v[204:207], v218 offset:896
	s_waitcnt lgkmcnt(0)
	v_pk_mul_f32 v[120:121], v[120:121], v[206:207]
	v_pk_mul_f32 v[118:119], v[118:119], v[204:205]
	v_pk_mul_f32 v[116:117], v[116:117], v[206:207]
	v_pk_mul_f32 v[114:115], v[114:115], v[204:205]
	ds_read_b128 v[204:207], v218 offset:960
	s_waitcnt lgkmcnt(0)
	s_barrier
; #define LAS __attribute__((address_space(3)))
; __device__ __forceinline__ unsigned cvt2(float a, float b) { f32x2s v = {a, b}; bf16x2_t r = __builtin_convertvector(v, bf16x2_t); return __builtin_bit_cast(unsigned, r); }
; #define SC_BAR() do { asm volatile("s_waitcnt lgkmcnt(0)" ::: "memory"); __builtin_amdgcn_s_barrier(); asm volatile("" ::: "memory"); } while (0)
; template <bool GLA>
; __device__ __forceinline__ void scan_item2(LAS unsigned char* lds, const bf16* Qd, const bf16* Kd, const bf16* V, bf16* O, const float* EG, int ldqk, int ldv, int b, int h, int dvs, float e_const, int tid) {
;     ...
;             for (int t = 0; t < 16; ++t) { if (GLA) { const f32x4 e4 = *(const LAS f32x4*)(lds + SC_EI + (16 * t + 4 * fq) * 4); st[t][0] = st[t][0] * e4; st[t][1] = st[t][1] * e4; } else { st[t][0] = st[t][0] * e_const; st[t][1] = st[t][1] * e_const; } }
;             SC_BAR();
; #pragma unroll
;             for (int ks = 0; ks < 2; ++ks) { bf16x8s ap[4];
; #pragma unroll
;                 for (int ti = 0; ti < 4; ++ti) ap[ti] = *(const LAS bf16x8s*)(lds + SC_PI + (16 * ti + fr) * SC_PS + (32 * ks + 8 * fq) * 2);
; #pragma unroll
;                 for (int ti = 0; ti < 4; ++ti)
; #pragma unroll
;                     for (int ct = 0; ct < 2; ++ct) oa[ti][ct] = __builtin_amdgcn_mfma_f32_16x16x32_bf16(bv[ks][ct], ap[ti], oa[ti][ct], 0, 0, 0); }
; #pragma unroll
;             for (int ti = 0; ti < 4; ++ti)
; #pragma unroll
;                 for (int ct = 0; ct < 2; ++ct) { v2u ow; ow.x = cvt2(oa[ti][ct][0], oa[ti][ct][1]); ow.y = cvt2(oa[ti][ct][2], oa[ti][ct][3]);
;                     *(v2u*)((char*)(obase + ((size_t)c * 64 + 16 * ti) * ldv + 16 * ct) + ooff) = ow; }
;         }
;         SC_BAR();
	s_waitcnt lgkmcnt(0)
	v_pk_mul_f32 v[128:129], v[128:129], v[206:207]
	v_pk_mul_f32 v[126:127], v[126:127], v[204:205]
	v_pk_mul_f32 v[124:125], v[124:125], v[206:207]
	v_pk_mul_f32 v[122:123], v[122:123], v[204:205]
	ds_read_b128 v[204:207], v219
	ds_read_b128 v[208:211], v219 offset:2560
	ds_read_b128 v[228:231], v219 offset:5120
	ds_read_b128 v[232:235], v219 offset:7680
	s_waitcnt lgkmcnt(3)
	v_mfma_f32_16x16x32_bf16 v[130:133], v[162:165], v[204:207], v[130:133]
	v_mfma_f32_16x16x32_bf16 v[158:161], v[170:173], v[204:207], v[158:161]
	s_waitcnt lgkmcnt(2)
	v_mfma_f32_16x16x32_bf16 v[134:137], v[162:165], v[208:211], v[134:137]
	v_mfma_f32_16x16x32_bf16 v[154:157], v[170:173], v[208:211], v[154:157]
	s_waitcnt lgkmcnt(1)
	v_mfma_f32_16x16x32_bf16 v[138:141], v[162:165], v[228:231], v[138:141]
	v_mfma_f32_16x16x32_bf16 v[150:153], v[170:173], v[228:231], v[150:153]
	s_waitcnt lgkmcnt(0)
	v_mfma_f32_16x16x32_bf16 v[142:145], v[162:165], v[232:235], v[142:145]
	v_mfma_f32_16x16x32_bf16 v[146:149], v[170:173], v[232:235], v[146:149]
	ds_read_b128 v[162:165], v219 offset:64
	ds_read_b128 v[170:173], v219 offset:2624
	ds_read_b128 v[204:207], v219 offset:5184
	ds_read_b128 v[208:211], v219 offset:7744
	s_waitcnt lgkmcnt(3)
	v_mfma_f32_16x16x32_bf16 v[130:133], v[166:169], v[162:165], v[130:133]
	v_mfma_f32_16x16x32_bf16 v[158:161], v[174:177], v[162:165], v[158:161]
	v_lshl_add_u64 v[162:163], v[190:191], 0, s[10:11]
	s_nop 5
	v_cvt_pk_bf16_f32 v130, v130, v131
	v_cvt_pk_bf16_f32 v131, v132, v133
	s_waitcnt lgkmcnt(2)
	v_mfma_f32_16x16x32_bf16 v[134:137], v[166:169], v[170:173], v[134:137]
	v_add_co_u32_e32 v132, vcc, s45, v162
	s_add_u32 s10, s10, 0x40000
	v_mfma_f32_16x16x32_bf16 v[154:157], v[174:177], v[170:173], v[154:157]
	v_addc_co_u32_e32 v133, vcc, 0, v163, vcc
	global_store_dwordx2 v[132:133], v[130:131], off
	v_cvt_pk_bf16_f32 v130, v158, v159
	v_cvt_pk_bf16_f32 v131, v160, v161
	s_waitcnt lgkmcnt(1)
	v_mfma_f32_16x16x32_bf16 v[138:141], v[166:169], v[204:207], v[138:141]
	global_store_dwordx2 v[132:133], v[130:131], off offset:32
	v_add_co_u32_e32 v132, vcc, s46, v162
	v_mfma_f32_16x16x32_bf16 v[150:153], v[174:177], v[204:207], v[150:153]
	v_cvt_pk_bf16_f32 v130, v134, v135
	v_cvt_pk_bf16_f32 v131, v136, v137
	v_addc_co_u32_e32 v133, vcc, 0, v163, vcc
	global_store_dwordx2 v[132:133], v[130:131], off
	v_cvt_pk_bf16_f32 v130, v154, v155
	v_cvt_pk_bf16_f32 v131, v156, v157
	s_waitcnt lgkmcnt(0)
	v_mfma_f32_16x16x32_bf16 v[142:145], v[166:169], v[208:211], v[142:145]
	global_store_dwordx2 v[132:133], v[130:131], off offset:32
	v_add_co_u32_e32 v132, vcc, s47, v162
	v_mfma_f32_16x16x32_bf16 v[146:149], v[174:177], v[208:211], v[146:149]
	v_cvt_pk_bf16_f32 v130, v138, v139
	v_cvt_pk_bf16_f32 v131, v140, v141
	v_addc_co_u32_e32 v133, vcc, 0, v163, vcc
	global_store_dwordx2 v[132:133], v[130:131], off
	v_cvt_pk_bf16_f32 v130, v150, v151
	v_cvt_pk_bf16_f32 v131, v152, v153
	global_store_dwordx2 v[132:133], v[130:131], off offset:32
	v_add_co_u32_e32 v132, vcc, s52, v162
	v_cvt_pk_bf16_f32 v130, v142, v143
	v_cvt_pk_bf16_f32 v131, v144, v145
	v_addc_co_u32_e32 v133, vcc, 0, v163, vcc
	s_addc_u32 s11, s11, 0
	global_store_dwordx2 v[132:133], v[130:131], off
	v_cvt_pk_bf16_f32 v130, v146, v147
	v_cvt_pk_bf16_f32 v131, v148, v149
	s_cmp_eq_u32 s10, 0x800000
	global_store_dwordx2 v[132:133], v[130:131], off offset:32
	s_cbranch_scc0 .LBB0_1911
	s_waitcnt lgkmcnt(0)
	s_barrier
	s_branch .LBB0_1907
